# zin GEMM: counted vmcnt at the first K-tile of later tiles so the previous epilogue's stores stay in flight
# baseline (speedup 1.0000x reference)
.Lgzin_noprio:
	s_and_b32 s4, s10, 7
	s_lshl_b32 s4, s4, 3
	s_bfe_u32 s32, s10, 0x30003
	s_or_b32 s4, s4, s32
	s_mul_i32 s4, s4, 0x50000
	s_add_u32 s2, s16, s4
	s_addc_u32 s3, s17, 0
	s_lshr_b32 s4, s10, 6
	s_mul_i32 s4, s4, 0x40000
	s_add_u32 s6, s18, s4
	s_addc_u32 s7, s19, 0
	s_add_u32 m0, s13, 0x0
	s_nop 0
	global_load_lds_dwordx4 v208, s[2:3]
	s_add_u32 m0, s13, 0x1000
	s_nop 0
	global_load_lds_dwordx4 v209, s[2:3]
	s_add_u32 m0, s13, 0x2000
	s_nop 0
	global_load_lds_dwordx4 v210, s[2:3]
	s_add_u32 m0, s13, 0x3000
	s_nop 0
	global_load_lds_dwordx4 v211, s[2:3]
	s_add_u32 m0, s13, 0x4000
	s_nop 0
	global_load_lds_dwordx4 v212, s[2:3]
	s_add_u32 m0, s13, 0x5000
	s_nop 0
	global_load_lds_dwordx4 v213, s[6:7]
	s_add_u32 m0, s13, 0x6000
	s_nop 0
	global_load_lds_dwordx4 v214, s[6:7]
	s_add_u32 m0, s13, 0x7000
	s_nop 0
	global_load_lds_dwordx4 v215, s[6:7]
	s_add_u32 m0, s13, 0x8000
	s_nop 0
	global_load_lds_dwordx4 v216, s[6:7]
	s_add_u32 s2, s2, 0x80
	s_addc_u32 s3, s3, 0
	s_add_u32 s6, s6, 0x80
	s_addc_u32 s7, s7, 0
	s_mov_b32 s48, 0

.Lgzin_pair:
	s_cmp_eq_u32 s12, 0x8
	s_cselect_b32 s4, s48, 0
	s_cmp_ge_u32 s4, 10
	s_cbranch_scc1 .Lgzin_w10
	s_waitcnt vmcnt(0)
	s_branch .Lgzin_wd

.Lgzin_wd:
	s_barrier
	ds_read_b128 v[80:83], v204 offset:0
	ds_read_b128 v[100:103], v206 offset:20480
	ds_read_b128 v[104:107], v206 offset:22528
	ds_read_b128 v[108:111], v206 offset:24576
	ds_read_b128 v[112:115], v206 offset:26624
	ds_read_b128 v[84:87], v204 offset:2048
	ds_read_b128 v[88:91], v204 offset:4096
	ds_read_b128 v[92:95], v204 offset:6144
	ds_read_b128 v[96:99], v204 offset:8192
	s_add_u32 m0, s13, 0xd100
	s_waitcnt lgkmcnt(7)
	v_mfma_f32_16x16x32_bf16 v[0:3], v[100:103], v[80:83], v[0:3]
	global_load_lds_dwordx4 v208, s[2:3]
	s_add_u32 m0, s13, 0xe100
	s_waitcnt lgkmcnt(6)
	v_mfma_f32_16x16x32_bf16 v[4:7], v[104:107], v[80:83], v[4:7]
	global_load_lds_dwordx4 v209, s[2:3]
	s_add_u32 m0, s13, 0xf100
	s_waitcnt lgkmcnt(5)
	v_mfma_f32_16x16x32_bf16 v[8:11], v[108:111], v[80:83], v[8:11]
	global_load_lds_dwordx4 v210, s[2:3]
	s_add_u32 m0, s13, 0x10100
	s_waitcnt lgkmcnt(4)
	v_mfma_f32_16x16x32_bf16 v[12:15], v[112:115], v[80:83], v[12:15]
	global_load_lds_dwordx4 v211, s[2:3]
	s_add_u32 m0, s13, 0x11100
	ds_read_b128 v[168:171], v205 offset:0
	ds_read_b128 v[188:191], v207 offset:20480
	ds_read_b128 v[192:195], v207 offset:22528
	ds_read_b128 v[196:199], v207 offset:24576
	ds_read_b128 v[200:203], v207 offset:26624
	s_waitcnt lgkmcnt(8)
	v_mfma_f32_16x16x32_bf16 v[16:19], v[100:103], v[84:87], v[16:19]
	global_load_lds_dwordx4 v212, s[2:3]
	s_add_u32 m0, s13, 0x9000
	v_mfma_f32_16x16x32_bf16 v[20:23], v[104:107], v[84:87], v[20:23]
	global_load_lds_dwordx4 v213, s[6:7]
	s_add_u32 m0, s13, 0xa000
	v_mfma_f32_16x16x32_bf16 v[24:27], v[108:111], v[84:87], v[24:27]
	global_load_lds_dwordx4 v214, s[6:7]
	s_add_u32 m0, s13, 0xb000
	v_mfma_f32_16x16x32_bf16 v[28:31], v[112:115], v[84:87], v[28:31]
	global_load_lds_dwordx4 v215, s[6:7]
	s_add_u32 m0, s13, 0xc000
	ds_read_b128 v[172:175], v205 offset:2048
	ds_read_b128 v[176:179], v205 offset:4096
	ds_read_b128 v[180:183], v205 offset:6144
	ds_read_b128 v[184:187], v205 offset:8192
	s_waitcnt lgkmcnt(11)
	v_mfma_f32_16x16x32_bf16 v[32:35], v[100:103], v[88:91], v[32:35]
	global_load_lds_dwordx4 v216, s[6:7]
	v_mfma_f32_16x16x32_bf16 v[36:39], v[104:107], v[88:91], v[36:39]
	v_mfma_f32_16x16x32_bf16 v[40:43], v[108:111], v[88:91], v[40:43]
	v_mfma_f32_16x16x32_bf16 v[44:47], v[112:115], v[88:91], v[44:47]
	s_waitcnt lgkmcnt(10)
	v_mfma_f32_16x16x32_bf16 v[48:51], v[100:103], v[92:95], v[48:51]
	v_mfma_f32_16x16x32_bf16 v[52:55], v[104:107], v[92:95], v[52:55]
	v_mfma_f32_16x16x32_bf16 v[56:59], v[108:111], v[92:95], v[56:59]
	v_mfma_f32_16x16x32_bf16 v[60:63], v[112:115], v[92:95], v[60:63]
	s_waitcnt lgkmcnt(9)
	v_mfma_f32_16x16x32_bf16 v[64:67], v[100:103], v[96:99], v[64:67]
	v_mfma_f32_16x16x32_bf16 v[68:71], v[104:107], v[96:99], v[68:71]
	v_mfma_f32_16x16x32_bf16 v[72:75], v[108:111], v[96:99], v[72:75]
	v_mfma_f32_16x16x32_bf16 v[76:79], v[112:115], v[96:99], v[76:79]
	s_waitcnt lgkmcnt(7)
	v_mfma_f32_16x16x32_bf16 v[0:3], v[188:191], v[168:171], v[0:3]
	s_waitcnt lgkmcnt(6)
	v_mfma_f32_16x16x32_bf16 v[4:7], v[192:195], v[168:171], v[4:7]
	s_waitcnt lgkmcnt(5)
	v_mfma_f32_16x16x32_bf16 v[8:11], v[196:199], v[168:171], v[8:11]
	s_waitcnt lgkmcnt(4)
	v_mfma_f32_16x16x32_bf16 v[12:15], v[200:203], v[168:171], v[12:15]
	s_waitcnt lgkmcnt(3)
	v_mfma_f32_16x16x32_bf16 v[16:19], v[188:191], v[172:175], v[16:19]
	v_mfma_f32_16x16x32_bf16 v[20:23], v[192:195], v[172:175], v[20:23]
	v_mfma_f32_16x16x32_bf16 v[24:27], v[196:199], v[172:175], v[24:27]
	v_mfma_f32_16x16x32_bf16 v[28:31], v[200:203], v[172:175], v[28:31]
	s_waitcnt lgkmcnt(2)
	v_mfma_f32_16x16x32_bf16 v[32:35], v[188:191], v[176:179], v[32:35]
	v_mfma_f32_16x16x32_bf16 v[36:39], v[192:195], v[176:179], v[36:39]
	v_mfma_f32_16x16x32_bf16 v[40:43], v[196:199], v[176:179], v[40:43]
	v_mfma_f32_16x16x32_bf16 v[44:47], v[200:203], v[176:179], v[44:47]
	s_waitcnt lgkmcnt(1)
	v_mfma_f32_16x16x32_bf16 v[48:51], v[188:191], v[180:183], v[48:51]
	v_mfma_f32_16x16x32_bf16 v[52:55], v[192:195], v[180:183], v[52:55]
	v_mfma_f32_16x16x32_bf16 v[56:59], v[196:199], v[180:183], v[56:59]
	v_mfma_f32_16x16x32_bf16 v[60:63], v[200:203], v[180:183], v[60:63]
	s_add_u32 s2, s2, 0x80
	s_addc_u32 s3, s3, 0
	s_add_u32 s6, s6, 0x80
	s_addc_u32 s7, s7, 0
	s_waitcnt lgkmcnt(0)
	v_mfma_f32_16x16x32_bf16 v[64:67], v[188:191], v[184:187], v[64:67]
	v_mfma_f32_16x16x32_bf16 v[68:71], v[192:195], v[184:187], v[68:71]
	v_mfma_f32_16x16x32_bf16 v[72:75], v[196:199], v[184:187], v[72:75]
	v_mfma_f32_16x16x32_bf16 v[76:79], v[200:203], v[184:187], v[76:79]
	s_cmp_eq_u32 s12, 1
	s_cselect_b32 s2, s20, s2
	s_cselect_b32 s3, s21, s3
	s_cselect_b32 s6, s22, s6
	s_cselect_b32 s7, s23, s7
	s_waitcnt vmcnt(0)
	s_barrier
	ds_read_b128 v[80:83], v204 offset:53504
	ds_read_b128 v[100:103], v206 offset:36864
	ds_read_b128 v[104:107], v206 offset:38912
	ds_read_b128 v[108:111], v206 offset:40960
	ds_read_b128 v[112:115], v206 offset:43008
	ds_read_b128 v[84:87], v204 offset:55552
	ds_read_b128 v[88:91], v204 offset:57600
	ds_read_b128 v[92:95], v204 offset:59648
	ds_read_b128 v[96:99], v204 offset:61696
	s_add_u32 m0, s13, 0x0
	s_waitcnt lgkmcnt(7)
	v_mfma_f32_16x16x32_bf16 v[0:3], v[100:103], v[80:83], v[0:3]
	global_load_lds_dwordx4 v208, s[2:3]
	s_add_u32 m0, s13, 0x1000
	s_waitcnt lgkmcnt(6)
	v_mfma_f32_16x16x32_bf16 v[4:7], v[104:107], v[80:83], v[4:7]
	global_load_lds_dwordx4 v209, s[2:3]
	s_add_u32 m0, s13, 0x2000
	s_waitcnt lgkmcnt(5)
	v_mfma_f32_16x16x32_bf16 v[8:11], v[108:111], v[80:83], v[8:11]
	global_load_lds_dwordx4 v210, s[2:3]
	s_add_u32 m0, s13, 0x3000
	s_waitcnt lgkmcnt(4)
	v_mfma_f32_16x16x32_bf16 v[12:15], v[112:115], v[80:83], v[12:15]
	global_load_lds_dwordx4 v211, s[2:3]
	s_add_u32 m0, s13, 0x4000
	ds_read_b128 v[168:171], v205 offset:53504
	ds_read_b128 v[188:191], v207 offset:36864
	ds_read_b128 v[192:195], v207 offset:38912
	ds_read_b128 v[196:199], v207 offset:40960
	ds_read_b128 v[200:203], v207 offset:43008
	s_waitcnt lgkmcnt(8)
	v_mfma_f32_16x16x32_bf16 v[16:19], v[100:103], v[84:87], v[16:19]
	global_load_lds_dwordx4 v212, s[2:3]
	s_add_u32 m0, s13, 0x5000
	v_mfma_f32_16x16x32_bf16 v[20:23], v[104:107], v[84:87], v[20:23]
	global_load_lds_dwordx4 v213, s[6:7]
	s_add_u32 m0, s13, 0x6000
	v_mfma_f32_16x16x32_bf16 v[24:27], v[108:111], v[84:87], v[24:27]
	global_load_lds_dwordx4 v214, s[6:7]
	s_add_u32 m0, s13, 0x7000
	v_mfma_f32_16x16x32_bf16 v[28:31], v[112:115], v[84:87], v[28:31]
	global_load_lds_dwordx4 v215, s[6:7]
	s_add_u32 m0, s13, 0x8000
	ds_read_b128 v[172:175], v205 offset:55552
	ds_read_b128 v[176:179], v205 offset:57600
	ds_read_b128 v[180:183], v205 offset:59648
	ds_read_b128 v[184:187], v205 offset:61696
	s_waitcnt lgkmcnt(11)
	v_mfma_f32_16x16x32_bf16 v[32:35], v[100:103], v[88:91], v[32:35]
	global_load_lds_dwordx4 v216, s[6:7]
	v_mfma_f32_16x16x32_bf16 v[36:39], v[104:107], v[88:91], v[36:39]
	v_mfma_f32_16x16x32_bf16 v[40:43], v[108:111], v[88:91], v[40:43]
	v_mfma_f32_16x16x32_bf16 v[44:47], v[112:115], v[88:91], v[44:47]
	s_waitcnt lgkmcnt(10)
	v_mfma_f32_16x16x32_bf16 v[48:51], v[100:103], v[92:95], v[48:51]
	v_mfma_f32_16x16x32_bf16 v[52:55], v[104:107], v[92:95], v[52:55]
	v_mfma_f32_16x16x32_bf16 v[56:59], v[108:111], v[92:95], v[56:59]
	v_mfma_f32_16x16x32_bf16 v[60:63], v[112:115], v[92:95], v[60:63]
	s_waitcnt lgkmcnt(9)
	v_mfma_f32_16x16x32_bf16 v[64:67], v[100:103], v[96:99], v[64:67]
	v_mfma_f32_16x16x32_bf16 v[68:71], v[104:107], v[96:99], v[68:71]
	v_mfma_f32_16x16x32_bf16 v[72:75], v[108:111], v[96:99], v[72:75]
	v_mfma_f32_16x16x32_bf16 v[76:79], v[112:115], v[96:99], v[76:79]
	s_waitcnt lgkmcnt(7)
	v_mfma_f32_16x16x32_bf16 v[0:3], v[188:191], v[168:171], v[0:3]
	s_waitcnt lgkmcnt(6)
	v_mfma_f32_16x16x32_bf16 v[4:7], v[192:195], v[168:171], v[4:7]
	s_waitcnt lgkmcnt(5)
	v_mfma_f32_16x16x32_bf16 v[8:11], v[196:199], v[168:171], v[8:11]
	s_waitcnt lgkmcnt(4)
	v_mfma_f32_16x16x32_bf16 v[12:15], v[200:203], v[168:171], v[12:15]
	s_waitcnt lgkmcnt(3)
	v_mfma_f32_16x16x32_bf16 v[16:19], v[188:191], v[172:175], v[16:19]
	v_mfma_f32_16x16x32_bf16 v[20:23], v[192:195], v[172:175], v[20:23]
	v_mfma_f32_16x16x32_bf16 v[24:27], v[196:199], v[172:175], v[24:27]
	v_mfma_f32_16x16x32_bf16 v[28:31], v[200:203], v[172:175], v[28:31]
	s_waitcnt lgkmcnt(2)
	v_mfma_f32_16x16x32_bf16 v[32:35], v[188:191], v[176:179], v[32:35]
	v_mfma_f32_16x16x32_bf16 v[36:39], v[192:195], v[176:179], v[36:39]
	v_mfma_f32_16x16x32_bf16 v[40:43], v[196:199], v[176:179], v[40:43]
	v_mfma_f32_16x16x32_bf16 v[44:47], v[200:203], v[176:179], v[44:47]
	s_waitcnt lgkmcnt(1)
	v_mfma_f32_16x16x32_bf16 v[48:51], v[188:191], v[180:183], v[48:51]
	v_mfma_f32_16x16x32_bf16 v[52:55], v[192:195], v[180:183], v[52:55]
	v_mfma_f32_16x16x32_bf16 v[56:59], v[196:199], v[180:183], v[56:59]
	v_mfma_f32_16x16x32_bf16 v[60:63], v[200:203], v[180:183], v[60:63]
	s_add_u32 s2, s2, 0x80
	s_addc_u32 s3, s3, 0
	s_add_u32 s6, s6, 0x80
	s_addc_u32 s7, s7, 0
	s_waitcnt lgkmcnt(0)
	v_mfma_f32_16x16x32_bf16 v[64:67], v[188:191], v[184:187], v[64:67]
	v_mfma_f32_16x16x32_bf16 v[68:71], v[192:195], v[184:187], v[68:71]
	v_mfma_f32_16x16x32_bf16 v[72:75], v[196:199], v[184:187], v[72:75]
	v_mfma_f32_16x16x32_bf16 v[76:79], v[200:203], v[184:187], v[76:79]
	s_sub_u32 s12, s12, 1
	s_cmp_lg_u32 s12, 0
	s_cbranch_scc1 .Lgzin_pair
	s_and_b32 s4, s10, 7
	s_lshl_b32 s4, s4, 3
	s_bfe_u32 s14, s10, 0x30003
	s_or_b32 s14, s14, s4
	s_lshr_b32 s15, s10, 6
	s_mul_i32 s44, s14, 0xa0
	s_mul_i32 s4, s35, 0x50
	s_add_u32 s4, s4, s44
	v_add_u32_e32 v219, s4, v222
	s_nop 7
	s_mov_b32 s48, 0
	s_lshl_b32 s46, s15, 7
	s_lshl_b32 s4, s36, 6
	s_add_u32 s46, s46, s4
	s_cmp_ge_u32 s46, 0xbc0
	s_cbranch_scc1 .Lgzin_z0_end
	s_cmp_lt_u32 s46, 0x200
	s_cbranch_scc1 .Lgzin_z0_q
	s_cmp_lt_u32 s46, 0x600
	s_cbranch_scc1 .Lgzin_z0_kv
	s_cmp_lt_u32 s46, 0x800
	s_cbranch_scc1 .Lgzin_z0_u
	s_add_u32 s48, s48, 10
	s_mul_i32 s4, s44, 0x2f00
	s_lshl_b32 s32, s46, 2
	s_add_u32 s4, s4, s32
	s_add_u32 s8, s74, s4
	s_addc_u32 s9, s75, 0
	global_store_dwordx4 v218, v[0:3], s[8:9]
	global_store_dwordx4 v218, v[4:7], s[8:9] offset:16
	s_add_u32 s8, s8, 0x2f000
	s_addc_u32 s9, s9, 0
	global_store_dwordx4 v218, v[16:19], s[8:9]
	global_store_dwordx4 v218, v[20:23], s[8:9] offset:16
	s_add_u32 s8, s8, 0x2f000
	s_addc_u32 s9, s9, 0
	global_store_dwordx4 v218, v[32:35], s[8:9]
	global_store_dwordx4 v218, v[36:39], s[8:9] offset:16
	s_add_u32 s8, s8, 0x2f000
	s_addc_u32 s9, s9, 0
	global_store_dwordx4 v218, v[48:51], s[8:9]
	global_store_dwordx4 v218, v[52:55], s[8:9] offset:16
	s_add_u32 s8, s8, 0x2f000
	s_addc_u32 s9, s9, 0
	global_store_dwordx4 v218, v[64:67], s[8:9]
	global_store_dwordx4 v218, v[68:71], s[8:9] offset:16
	s_branch .Lgzin_z0_end
.Lgzin_z0_q:
	s_add_u32 s48, s48, 5
	s_lshl_b32 s4, s44, 10
	s_lshl_b32 s32, s46, 1
	s_add_u32 s4, s4, s32
	s_add_u32 s8, s68, s4
	s_addc_u32 s9, s69, 0
	v_cvt_pk_bf16_f32 v80, v0, v1
	v_cvt_pk_bf16_f32 v81, v2, v3
	v_cvt_pk_bf16_f32 v82, v4, v5
	v_cvt_pk_bf16_f32 v83, v6, v7
	global_store_dwordx4 v217, v[80:83], s[8:9]
	s_add_u32 s8, s8, 0x4000
	s_addc_u32 s9, s9, 0
	v_cvt_pk_bf16_f32 v84, v16, v17
	v_cvt_pk_bf16_f32 v85, v18, v19
	v_cvt_pk_bf16_f32 v86, v20, v21
	v_cvt_pk_bf16_f32 v87, v22, v23
	global_store_dwordx4 v217, v[84:87], s[8:9]
	s_add_u32 s8, s8, 0x4000
	s_addc_u32 s9, s9, 0
	v_cvt_pk_bf16_f32 v88, v32, v33
	v_cvt_pk_bf16_f32 v89, v34, v35
	v_cvt_pk_bf16_f32 v90, v36, v37
	v_cvt_pk_bf16_f32 v91, v38, v39
	global_store_dwordx4 v217, v[88:91], s[8:9]
	s_add_u32 s8, s8, 0x4000
	s_addc_u32 s9, s9, 0
	v_cvt_pk_bf16_f32 v92, v48, v49
	v_cvt_pk_bf16_f32 v93, v50, v51
	v_cvt_pk_bf16_f32 v94, v52, v53
	v_cvt_pk_bf16_f32 v95, v54, v55
	global_store_dwordx4 v217, v[92:95], s[8:9]
	s_add_u32 s8, s8, 0x4000
	s_addc_u32 s9, s9, 0
	v_cvt_pk_bf16_f32 v96, v64, v65
	v_cvt_pk_bf16_f32 v97, v66, v67
	v_cvt_pk_bf16_f32 v98, v68, v69
	v_cvt_pk_bf16_f32 v99, v70, v71
	global_store_dwordx4 v217, v[96:99], s[8:9]
	s_branch .Lgzin_z0_end
.Lgzin_z0_u:
	s_add_u32 s48, s48, 5
	s_lshl_b32 s4, s44, 10
	s_sub_u32 s32, s46, 0x600
	s_lshl_b32 s32, s32, 1
	s_add_u32 s4, s4, s32
	s_add_u32 s8, s70, s4
	s_addc_u32 s9, s71, 0
	v_cvt_pk_bf16_f32 v80, v0, v1
	v_cvt_pk_bf16_f32 v81, v2, v3
	v_cvt_pk_bf16_f32 v82, v4, v5
	v_cvt_pk_bf16_f32 v83, v6, v7
	global_store_dwordx4 v217, v[80:83], s[8:9]
	s_add_u32 s8, s8, 0x4000
	s_addc_u32 s9, s9, 0
	v_cvt_pk_bf16_f32 v84, v16, v17
	v_cvt_pk_bf16_f32 v85, v18, v19
	v_cvt_pk_bf16_f32 v86, v20, v21
	v_cvt_pk_bf16_f32 v87, v22, v23
	global_store_dwordx4 v217, v[84:87], s[8:9]
	s_add_u32 s8, s8, 0x4000
	s_addc_u32 s9, s9, 0
	v_cvt_pk_bf16_f32 v88, v32, v33
	v_cvt_pk_bf16_f32 v89, v34, v35
	v_cvt_pk_bf16_f32 v90, v36, v37
	v_cvt_pk_bf16_f32 v91, v38, v39
	global_store_dwordx4 v217, v[88:91], s[8:9]
	s_add_u32 s8, s8, 0x4000
	s_addc_u32 s9, s9, 0
	v_cvt_pk_bf16_f32 v92, v48, v49
	v_cvt_pk_bf16_f32 v93, v50, v51
	v_cvt_pk_bf16_f32 v94, v52, v53
	v_cvt_pk_bf16_f32 v95, v54, v55
	global_store_dwordx4 v217, v[92:95], s[8:9]
	s_add_u32 s8, s8, 0x4000
	s_addc_u32 s9, s9, 0
	v_cvt_pk_bf16_f32 v96, v64, v65
	v_cvt_pk_bf16_f32 v97, v66, v67
	v_cvt_pk_bf16_f32 v98, v68, v69
	v_cvt_pk_bf16_f32 v99, v70, v71
	global_store_dwordx4 v217, v[96:99], s[8:9]
	s_branch .Lgzin_z0_end
.Lgzin_z0_kv:
	s_add_u32 s48, s48, 10
	s_mul_i32 s4, s44, 0x2f00
	s_lshl_b32 s32, s46, 2
	s_add_u32 s4, s4, s32
	s_add_u32 s8, s74, s4
	s_addc_u32 s9, s75, 0
	v_readlane_b32 s52, v164, 63
	v_readlane_b32 s53, v163, 0
	v_readlane_b32 s54, v163, 1
	v_readlane_b32 s55, v163, 2
	s_cmp_lt_u32 s46, 0x400
	s_cselect_b32 s52, s52, s54
	s_cselect_b32 s53, s53, s55
	s_and_b32 s4, s46, 0x1ff
	s_lshl_b32 s4, s4, 2
	s_lshl_b32 s32, s34, 19
	s_add_u32 s4, s4, s32
	s_add_u32 s52, s52, s4
	s_addc_u32 s53, s53, 0
	v_add_u32_e32 v235, 0, v219
	v_and_b32_e32 v236, 0xffffff00, v235
	v_lshlrev_b32_e32 v236, 12, v236
	v_and_b32_e32 v237, 0xff, v235
	v_lshl_add_u32 v236, v237, 11, v236
	v_lshl_add_u32 v236, v223, 5, v236
	v_cmp_gt_u32_e32 vcc, 0x2000, v235
	s_and_saveexec_b64 s[50:51], vcc
	global_store_dwordx4 v236, v[0:3], s[52:53]
	global_store_dwordx4 v236, v[4:7], s[52:53] offset:16
	s_andn2_b64 exec, s[50:51], exec
	global_store_dwordx4 v218, v[0:3], s[8:9]
	global_store_dwordx4 v218, v[4:7], s[8:9] offset:16
	s_mov_b64 exec, s[50:51]
	s_add_u32 s8, s8, 0x2f000
	s_addc_u32 s9, s9, 0
	v_add_u32_e32 v235, 16, v219
	v_and_b32_e32 v236, 0xffffff00, v235
	v_lshlrev_b32_e32 v236, 12, v236
	v_and_b32_e32 v237, 0xff, v235
	v_lshl_add_u32 v236, v237, 11, v236
	v_lshl_add_u32 v236, v223, 5, v236
	v_cmp_gt_u32_e32 vcc, 0x2000, v235
	s_and_saveexec_b64 s[50:51], vcc
	global_store_dwordx4 v236, v[16:19], s[52:53]
	global_store_dwordx4 v236, v[20:23], s[52:53] offset:16
	s_andn2_b64 exec, s[50:51], exec
	global_store_dwordx4 v218, v[16:19], s[8:9]
	global_store_dwordx4 v218, v[20:23], s[8:9] offset:16
	s_mov_b64 exec, s[50:51]
	s_add_u32 s8, s8, 0x2f000
	s_addc_u32 s9, s9, 0
	v_add_u32_e32 v235, 32, v219
	v_and_b32_e32 v236, 0xffffff00, v235
	v_lshlrev_b32_e32 v236, 12, v236
	v_and_b32_e32 v237, 0xff, v235
	v_lshl_add_u32 v236, v237, 11, v236
	v_lshl_add_u32 v236, v223, 5, v236
	v_cmp_gt_u32_e32 vcc, 0x2000, v235
	s_and_saveexec_b64 s[50:51], vcc
	global_store_dwordx4 v236, v[32:35], s[52:53]
	global_store_dwordx4 v236, v[36:39], s[52:53] offset:16
	s_andn2_b64 exec, s[50:51], exec
	global_store_dwordx4 v218, v[32:35], s[8:9]
	global_store_dwordx4 v218, v[36:39], s[8:9] offset:16
	s_mov_b64 exec, s[50:51]
	s_add_u32 s8, s8, 0x2f000
	s_addc_u32 s9, s9, 0
	v_add_u32_e32 v235, 48, v219
	v_and_b32_e32 v236, 0xffffff00, v235
	v_lshlrev_b32_e32 v236, 12, v236
	v_and_b32_e32 v237, 0xff, v235
	v_lshl_add_u32 v236, v237, 11, v236
	v_lshl_add_u32 v236, v223, 5, v236
	v_cmp_gt_u32_e32 vcc, 0x2000, v235
	s_and_saveexec_b64 s[50:51], vcc
	global_store_dwordx4 v236, v[48:51], s[52:53]
	global_store_dwordx4 v236, v[52:55], s[52:53] offset:16
	s_andn2_b64 exec, s[50:51], exec
	global_store_dwordx4 v218, v[48:51], s[8:9]
	global_store_dwordx4 v218, v[52:55], s[8:9] offset:16
	s_mov_b64 exec, s[50:51]
	s_add_u32 s8, s8, 0x2f000
	s_addc_u32 s9, s9, 0
	v_add_u32_e32 v235, 64, v219
	v_and_b32_e32 v236, 0xffffff00, v235
	v_lshlrev_b32_e32 v236, 12, v236
	v_and_b32_e32 v237, 0xff, v235
	v_lshl_add_u32 v236, v237, 11, v236
	v_lshl_add_u32 v236, v223, 5, v236
	v_cmp_gt_u32_e32 vcc, 0x2000, v235
	s_and_saveexec_b64 s[50:51], vcc
	global_store_dwordx4 v236, v[64:67], s[52:53]
	global_store_dwordx4 v236, v[68:71], s[52:53] offset:16
	s_andn2_b64 exec, s[50:51], exec
	global_store_dwordx4 v218, v[64:67], s[8:9]
	global_store_dwordx4 v218, v[68:71], s[8:9] offset:16
	s_mov_b64 exec, s[50:51]
.Lgzin_z0_end:
	s_lshl_b32 s46, s15, 7
	s_lshl_b32 s4, s36, 6
	s_add_u32 s46, s46, s4
	s_add_u32 s46, s46, 32
	s_cmp_ge_u32 s46, 0xbc0
	s_cbranch_scc1 .Lgzin_z1_end
	s_cmp_lt_u32 s46, 0x200
	s_cbranch_scc1 .Lgzin_z1_q
	s_cmp_lt_u32 s46, 0x600
	s_cbranch_scc1 .Lgzin_z1_kv
	s_cmp_lt_u32 s46, 0x800
	s_cbranch_scc1 .Lgzin_z1_u
	s_add_u32 s48, s48, 10
	s_mul_i32 s4, s44, 0x2f00
	s_lshl_b32 s32, s46, 2
	s_add_u32 s4, s4, s32
	s_add_u32 s8, s74, s4
	s_addc_u32 s9, s75, 0
	global_store_dwordx4 v218, v[8:11], s[8:9]
	global_store_dwordx4 v218, v[12:15], s[8:9] offset:16
	s_add_u32 s8, s8, 0x2f000
	s_addc_u32 s9, s9, 0
	global_store_dwordx4 v218, v[24:27], s[8:9]
	global_store_dwordx4 v218, v[28:31], s[8:9] offset:16
	s_add_u32 s8, s8, 0x2f000
	s_addc_u32 s9, s9, 0
	global_store_dwordx4 v218, v[40:43], s[8:9]
	global_store_dwordx4 v218, v[44:47], s[8:9] offset:16
	s_add_u32 s8, s8, 0x2f000
	s_addc_u32 s9, s9, 0
	global_store_dwordx4 v218, v[56:59], s[8:9]
	global_store_dwordx4 v218, v[60:63], s[8:9] offset:16
	s_add_u32 s8, s8, 0x2f000
	s_addc_u32 s9, s9, 0
	global_store_dwordx4 v218, v[72:75], s[8:9]
	global_store_dwordx4 v218, v[76:79], s[8:9] offset:16
	s_branch .Lgzin_z1_end
.Lgzin_z1_q:
	s_add_u32 s48, s48, 5
	s_lshl_b32 s4, s44, 10
	s_lshl_b32 s32, s46, 1
	s_add_u32 s4, s4, s32
	s_add_u32 s8, s68, s4
	s_addc_u32 s9, s69, 0
	v_cvt_pk_bf16_f32 v80, v8, v9
	v_cvt_pk_bf16_f32 v81, v10, v11
	v_cvt_pk_bf16_f32 v82, v12, v13
	v_cvt_pk_bf16_f32 v83, v14, v15
	global_store_dwordx4 v217, v[80:83], s[8:9]
	s_add_u32 s8, s8, 0x4000
	s_addc_u32 s9, s9, 0
	v_cvt_pk_bf16_f32 v84, v24, v25
	v_cvt_pk_bf16_f32 v85, v26, v27
	v_cvt_pk_bf16_f32 v86, v28, v29
	v_cvt_pk_bf16_f32 v87, v30, v31
	global_store_dwordx4 v217, v[84:87], s[8:9]
	s_add_u32 s8, s8, 0x4000
	s_addc_u32 s9, s9, 0
	v_cvt_pk_bf16_f32 v88, v40, v41
	v_cvt_pk_bf16_f32 v89, v42, v43
	v_cvt_pk_bf16_f32 v90, v44, v45
	v_cvt_pk_bf16_f32 v91, v46, v47
	global_store_dwordx4 v217, v[88:91], s[8:9]
	s_add_u32 s8, s8, 0x4000
	s_addc_u32 s9, s9, 0
	v_cvt_pk_bf16_f32 v92, v56, v57
	v_cvt_pk_bf16_f32 v93, v58, v59
	v_cvt_pk_bf16_f32 v94, v60, v61
	v_cvt_pk_bf16_f32 v95, v62, v63
	global_store_dwordx4 v217, v[92:95], s[8:9]
	s_add_u32 s8, s8, 0x4000
	s_addc_u32 s9, s9, 0
	v_cvt_pk_bf16_f32 v96, v72, v73
	v_cvt_pk_bf16_f32 v97, v74, v75
	v_cvt_pk_bf16_f32 v98, v76, v77
	v_cvt_pk_bf16_f32 v99, v78, v79
	global_store_dwordx4 v217, v[96:99], s[8:9]
	s_branch .Lgzin_z1_end
.Lgzin_z1_u:
	s_add_u32 s48, s48, 5
	s_lshl_b32 s4, s44, 10
	s_sub_u32 s32, s46, 0x600
	s_lshl_b32 s32, s32, 1
	s_add_u32 s4, s4, s32
	s_add_u32 s8, s70, s4
	s_addc_u32 s9, s71, 0
	v_cvt_pk_bf16_f32 v80, v8, v9
	v_cvt_pk_bf16_f32 v81, v10, v11
	v_cvt_pk_bf16_f32 v82, v12, v13
	v_cvt_pk_bf16_f32 v83, v14, v15
	global_store_dwordx4 v217, v[80:83], s[8:9]
	s_add_u32 s8, s8, 0x4000
	s_addc_u32 s9, s9, 0
	v_cvt_pk_bf16_f32 v84, v24, v25
	v_cvt_pk_bf16_f32 v85, v26, v27
	v_cvt_pk_bf16_f32 v86, v28, v29
	v_cvt_pk_bf16_f32 v87, v30, v31
	global_store_dwordx4 v217, v[84:87], s[8:9]
	s_add_u32 s8, s8, 0x4000
	s_addc_u32 s9, s9, 0
	v_cvt_pk_bf16_f32 v88, v40, v41
	v_cvt_pk_bf16_f32 v89, v42, v43
	v_cvt_pk_bf16_f32 v90, v44, v45
	v_cvt_pk_bf16_f32 v91, v46, v47
	global_store_dwordx4 v217, v[88:91], s[8:9]
	s_add_u32 s8, s8, 0x4000
	s_addc_u32 s9, s9, 0
	v_cvt_pk_bf16_f32 v92, v56, v57
	v_cvt_pk_bf16_f32 v93, v58, v59
	v_cvt_pk_bf16_f32 v94, v60, v61
	v_cvt_pk_bf16_f32 v95, v62, v63
	global_store_dwordx4 v217, v[92:95], s[8:9]
	s_add_u32 s8, s8, 0x4000
	s_addc_u32 s9, s9, 0
	v_cvt_pk_bf16_f32 v96, v72, v73
	v_cvt_pk_bf16_f32 v97, v74, v75
	v_cvt_pk_bf16_f32 v98, v76, v77
	v_cvt_pk_bf16_f32 v99, v78, v79
	global_store_dwordx4 v217, v[96:99], s[8:9]
	s_branch .Lgzin_z1_end
.Lgzin_z1_kv:
	s_add_u32 s48, s48, 10
	s_mul_i32 s4, s44, 0x2f00
	s_lshl_b32 s32, s46, 2
	s_add_u32 s4, s4, s32
	s_add_u32 s8, s74, s4
	s_addc_u32 s9, s75, 0
	v_readlane_b32 s52, v164, 63
	v_readlane_b32 s53, v163, 0
	v_readlane_b32 s54, v163, 1
	v_readlane_b32 s55, v163, 2
	s_cmp_lt_u32 s46, 0x400
	s_cselect_b32 s52, s52, s54
	s_cselect_b32 s53, s53, s55
	s_and_b32 s4, s46, 0x1ff
	s_lshl_b32 s4, s4, 2
	s_lshl_b32 s32, s34, 19
	s_add_u32 s4, s4, s32
	s_add_u32 s52, s52, s4
	s_addc_u32 s53, s53, 0
	v_add_u32_e32 v235, 0, v219
	v_and_b32_e32 v236, 0xffffff00, v235
	v_lshlrev_b32_e32 v236, 12, v236
	v_and_b32_e32 v237, 0xff, v235
	v_lshl_add_u32 v236, v237, 11, v236
	v_lshl_add_u32 v236, v223, 5, v236
	v_cmp_gt_u32_e32 vcc, 0x2000, v235
	s_and_saveexec_b64 s[50:51], vcc
	global_store_dwordx4 v236, v[8:11], s[52:53]
	global_store_dwordx4 v236, v[12:15], s[52:53] offset:16
	s_andn2_b64 exec, s[50:51], exec
	global_store_dwordx4 v218, v[8:11], s[8:9]
	global_store_dwordx4 v218, v[12:15], s[8:9] offset:16
	s_mov_b64 exec, s[50:51]
	s_add_u32 s8, s8, 0x2f000
	s_addc_u32 s9, s9, 0
	v_add_u32_e32 v235, 16, v219
	v_and_b32_e32 v236, 0xffffff00, v235
	v_lshlrev_b32_e32 v236, 12, v236
	v_and_b32_e32 v237, 0xff, v235
	v_lshl_add_u32 v236, v237, 11, v236
	v_lshl_add_u32 v236, v223, 5, v236
	v_cmp_gt_u32_e32 vcc, 0x2000, v235
	s_and_saveexec_b64 s[50:51], vcc
	global_store_dwordx4 v236, v[24:27], s[52:53]
	global_store_dwordx4 v236, v[28:31], s[52:53] offset:16
	s_andn2_b64 exec, s[50:51], exec
	global_store_dwordx4 v218, v[24:27], s[8:9]
	global_store_dwordx4 v218, v[28:31], s[8:9] offset:16
	s_mov_b64 exec, s[50:51]
	s_add_u32 s8, s8, 0x2f000
	s_addc_u32 s9, s9, 0
	v_add_u32_e32 v235, 32, v219
	v_and_b32_e32 v236, 0xffffff00, v235
	v_lshlrev_b32_e32 v236, 12, v236
	v_and_b32_e32 v237, 0xff, v235
	v_lshl_add_u32 v236, v237, 11, v236
	v_lshl_add_u32 v236, v223, 5, v236
	v_cmp_gt_u32_e32 vcc, 0x2000, v235
	s_and_saveexec_b64 s[50:51], vcc
	global_store_dwordx4 v236, v[40:43], s[52:53]
	global_store_dwordx4 v236, v[44:47], s[52:53] offset:16
	s_andn2_b64 exec, s[50:51], exec
	global_store_dwordx4 v218, v[40:43], s[8:9]
	global_store_dwordx4 v218, v[44:47], s[8:9] offset:16
	s_mov_b64 exec, s[50:51]
	s_add_u32 s8, s8, 0x2f000
	s_addc_u32 s9, s9, 0
	v_add_u32_e32 v235, 48, v219
	v_and_b32_e32 v236, 0xffffff00, v235
	v_lshlrev_b32_e32 v236, 12, v236
	v_and_b32_e32 v237, 0xff, v235
	v_lshl_add_u32 v236, v237, 11, v236
	v_lshl_add_u32 v236, v223, 5, v236
	v_cmp_gt_u32_e32 vcc, 0x2000, v235
	s_and_saveexec_b64 s[50:51], vcc
	global_store_dwordx4 v236, v[56:59], s[52:53]
	global_store_dwordx4 v236, v[60:63], s[52:53] offset:16
	s_andn2_b64 exec, s[50:51], exec
	global_store_dwordx4 v218, v[56:59], s[8:9]
	global_store_dwordx4 v218, v[60:63], s[8:9] offset:16
	s_mov_b64 exec, s[50:51]
	s_add_u32 s8, s8, 0x2f000
	s_addc_u32 s9, s9, 0
	v_add_u32_e32 v235, 64, v219
	v_and_b32_e32 v236, 0xffffff00, v235
	v_lshlrev_b32_e32 v236, 12, v236
	v_and_b32_e32 v237, 0xff, v235
	v_lshl_add_u32 v236, v237, 11, v236
	v_lshl_add_u32 v236, v223, 5, v236
	v_cmp_gt_u32_e32 vcc, 0x2000, v235
	s_and_saveexec_b64 s[50:51], vcc
	global_store_dwordx4 v236, v[72:75], s[52:53]
	global_store_dwordx4 v236, v[76:79], s[52:53] offset:16
	s_andn2_b64 exec, s[50:51], exec
	global_store_dwordx4 v218, v[72:75], s[8:9]
	global_store_dwordx4 v218, v[76:79], s[8:9] offset:16
	s_mov_b64 exec, s[50:51]
